# v56 + first K-iteration peeled with C=0 MFMAs, accumulator zeroing removed
# speedup vs baseline: 1.0454x; 1.0051x over previous
.LBB0_158:
	s_ashr_i32 s15, s14, 31
	s_lshl_b64 s[16:17], s[14:15], 20
	s_add_u32 s16, s3, s16
	s_addc_u32 s17, s28, s17
	s_and_b64 s[18:19], s[4:5], exec
	s_cselect_b32 s15, s17, s23
	s_cselect_b32 s46, s16, s22
	s_ashr_i32 s13, s12, 31
	s_lshl_b64 s[18:19], s[12:13], 20
	s_add_u32 s18, s29, s18
	s_addc_u32 s19, s30, s19
	s_and_b64 s[26:27], s[4:5], exec
	s_cselect_b32 s13, s19, s25
	s_cselect_b32 s47, s18, s24
	s_add_u32 s22, s22, 0x80080
	s_addc_u32 s23, s23, 0
	s_add_u32 s48, s24, 0x100
	s_addc_u32 s49, s25, 0
	s_mov_b32 s50, -2
	s_add_u32 s0, s22, 0xfff80080
	s_addc_u32 s1, s23, -1
	s_add_i32 s51, 0, 0x10000
	s_cmp_eq_u32 s50, 28
	s_cselect_b32 s27, s15, s1
	s_cselect_b32 s26, s46, s0
	v_add_u32_e32 v140, s51, v143
	s_cselect_b32 s25, s13, s49
	s_cselect_b32 s24, s47, s48
	s_add_i32 s0, 0, 0x14000
	ds_read_b128 v[146:149], v140
	ds_read_b128 v[150:153], v140 offset:1024
	ds_read_b128 v[154:157], v140 offset:2048
	ds_read_b128 v[158:161], v140 offset:3072
	v_add_u32_e32 v140, s0, v143
	ds_read_b128 v[162:165], v140
	ds_read_b128 v[166:169], v140 offset:1024
	ds_read_b128 v[170:173], v140 offset:2048
	ds_read_b128 v[174:177], v140 offset:3072
	s_add_i32 m0, s35, 0xc000
	ds_read_b128 v[178:181], v144
	ds_read_b128 v[182:185], v144 offset:1024
	ds_read_b128 v[192:195], v144 offset:2048
	ds_read_b128 v[196:199], v144 offset:3072
	ds_read_b128 v[200:203], v144 offset:4096
	ds_read_b128 v[204:207], v144 offset:5120
	ds_read_b128 v[208:211], v144 offset:6144
	ds_read_b128 v[212:215], v144 offset:7168
	global_load_lds_dwordx4 v136, s[22:23]
	s_add_i32 m0, s35, 0xe000
	s_nop 0
	global_load_lds_dwordx4 v138, s[22:23]
	s_waitcnt vmcnt(8)
	s_waitcnt lgkmcnt(0)
	s_setprio 1
	s_barrier

	v_mfma_f32_16x16x32_bf16 v[126:129], v[146:149], v[178:181], 0
	v_mfma_f32_16x16x32_bf16 v[126:129], v[150:153], v[182:185], v[126:129]
	v_mfma_f32_16x16x32_bf16 v[118:121], v[158:161], v[182:185], 0
	v_mfma_f32_16x16x32_bf16 v[118:121], v[154:157], v[178:181], v[118:121]
	v_mfma_f32_16x16x32_bf16 v[102:105], v[154:157], v[192:195], 0
	v_mfma_f32_16x16x32_bf16 v[102:105], v[158:161], v[196:199], v[102:105]
	v_mfma_f32_16x16x32_bf16 v[110:113], v[150:153], v[196:199], 0
	v_mfma_f32_16x16x32_bf16 v[110:113], v[146:149], v[192:195], v[110:113]
	v_mfma_f32_16x16x32_bf16 v[94:97], v[146:149], v[200:203], 0
	v_mfma_f32_16x16x32_bf16 v[94:97], v[150:153], v[204:207], v[94:97]
	v_mfma_f32_16x16x32_bf16 v[86:89], v[158:161], v[204:207], 0
	v_mfma_f32_16x16x32_bf16 v[86:89], v[154:157], v[200:203], v[86:89]
	v_mfma_f32_16x16x32_bf16 v[70:73], v[154:157], v[208:211], 0
	v_mfma_f32_16x16x32_bf16 v[70:73], v[158:161], v[212:215], v[70:73]
	v_mfma_f32_16x16x32_bf16 v[78:81], v[150:153], v[212:215], 0
	v_mfma_f32_16x16x32_bf16 v[78:81], v[146:149], v[208:211], v[78:81]


	v_mfma_f32_16x16x32_bf16 v[122:125], v[162:165], v[178:181], 0
	v_mfma_f32_16x16x32_bf16 v[122:125], v[166:169], v[182:185], v[122:125]
	v_mfma_f32_16x16x32_bf16 v[114:117], v[174:177], v[182:185], 0
	v_mfma_f32_16x16x32_bf16 v[114:117], v[170:173], v[178:181], v[114:117]
	v_mfma_f32_16x16x32_bf16 v[98:101], v[170:173], v[192:195], 0
	v_mfma_f32_16x16x32_bf16 v[98:101], v[174:177], v[196:199], v[98:101]
	v_mfma_f32_16x16x32_bf16 v[106:109], v[166:169], v[196:199], 0
	v_mfma_f32_16x16x32_bf16 v[106:109], v[162:165], v[192:195], v[106:109]
	v_mfma_f32_16x16x32_bf16 v[90:93], v[162:165], v[200:203], 0
	v_mfma_f32_16x16x32_bf16 v[90:93], v[166:169], v[204:207], v[90:93]
	v_mfma_f32_16x16x32_bf16 v[82:85], v[174:177], v[204:207], 0
	v_mfma_f32_16x16x32_bf16 v[82:85], v[170:173], v[200:203], v[82:85]
	v_mfma_f32_16x16x32_bf16 v[66:69], v[170:173], v[208:211], 0
	v_mfma_f32_16x16x32_bf16 v[66:69], v[174:177], v[212:215], v[66:69]
	v_mfma_f32_16x16x32_bf16 v[74:77], v[166:169], v[212:215], 0
	v_mfma_f32_16x16x32_bf16 v[74:77], v[162:165], v[208:211], v[74:77]
	s_barrier
	s_setprio 0
	s_add_i32 s1, s51, s31
	s_mov_b32 m0, s1
	ds_read_b128 v[178:181], v144 offset:16384
	ds_read_b128 v[182:185], v144 offset:17408
	ds_read_b128 v[192:195], v144 offset:18432
	ds_read_b128 v[196:199], v144 offset:19456
	ds_read_b128 v[200:203], v144 offset:20480
	ds_read_b128 v[204:207], v144 offset:21504
	ds_read_b128 v[208:211], v144 offset:22528
	ds_read_b128 v[212:215], v144 offset:23552
	global_load_lds_dwordx4 v186, s[24:25]
	s_add_i32 m0, s1, 0x2000
	s_add_u32 s52, s24, 0x80000
	s_addc_u32 s53, s25, 0
	s_add_i32 s0, s0, s31
	global_load_lds_dwordx4 v130, s[24:25]
	s_mov_b32 m0, s0
	s_nop 0
	global_load_lds_dwordx4 v186, s[52:53]
	s_add_i32 m0, s0, 0x2000
	s_nop 0
	global_load_lds_dwordx4 v130, s[52:53]
	s_mov_b32 m0, s35
	s_nop 0
	global_load_lds_dwordx4 v134, s[26:27]
	s_mov_b32 m0, s36
	s_nop 0
	global_load_lds_dwordx4 v132, s[26:27]
	s_waitcnt vmcnt(8)
	s_waitcnt lgkmcnt(0)
	s_setprio 1
	s_barrier

	v_mfma_f32_16x16x32_bf16 v[62:65], v[146:149], v[178:181], 0
	v_mfma_f32_16x16x32_bf16 v[62:65], v[150:153], v[182:185], v[62:65]
	v_mfma_f32_16x16x32_bf16 v[54:57], v[158:161], v[182:185], 0
	v_mfma_f32_16x16x32_bf16 v[54:57], v[154:157], v[178:181], v[54:57]
	v_mfma_f32_16x16x32_bf16 v[38:41], v[154:157], v[192:195], 0
	v_mfma_f32_16x16x32_bf16 v[38:41], v[158:161], v[196:199], v[38:41]
	v_mfma_f32_16x16x32_bf16 v[46:49], v[150:153], v[196:199], 0
	v_mfma_f32_16x16x32_bf16 v[46:49], v[146:149], v[192:195], v[46:49]
	v_mfma_f32_16x16x32_bf16 v[30:33], v[146:149], v[200:203], 0
	v_mfma_f32_16x16x32_bf16 v[30:33], v[150:153], v[204:207], v[30:33]
	v_mfma_f32_16x16x32_bf16 v[22:25], v[158:161], v[204:207], 0
	v_mfma_f32_16x16x32_bf16 v[22:25], v[154:157], v[200:203], v[22:25]
	v_mfma_f32_16x16x32_bf16 v[6:9], v[154:157], v[208:211], 0
	v_mfma_f32_16x16x32_bf16 v[6:9], v[158:161], v[212:215], v[6:9]
	v_mfma_f32_16x16x32_bf16 v[14:17], v[150:153], v[212:215], 0
	v_mfma_f32_16x16x32_bf16 v[14:17], v[146:149], v[208:211], v[14:17]


	v_mfma_f32_16x16x32_bf16 v[58:61], v[162:165], v[178:181], 0
	v_mfma_f32_16x16x32_bf16 v[58:61], v[166:169], v[182:185], v[58:61]
	v_mfma_f32_16x16x32_bf16 v[50:53], v[174:177], v[182:185], 0
	v_mfma_f32_16x16x32_bf16 v[50:53], v[170:173], v[178:181], v[50:53]
	v_mfma_f32_16x16x32_bf16 v[34:37], v[170:173], v[192:195], 0
	v_mfma_f32_16x16x32_bf16 v[34:37], v[174:177], v[196:199], v[34:37]
	v_mfma_f32_16x16x32_bf16 v[42:45], v[166:169], v[196:199], 0
	v_mfma_f32_16x16x32_bf16 v[42:45], v[162:165], v[192:195], v[42:45]
	v_mfma_f32_16x16x32_bf16 v[26:29], v[162:165], v[200:203], 0
	v_mfma_f32_16x16x32_bf16 v[26:29], v[166:169], v[204:207], v[26:29]
	v_mfma_f32_16x16x32_bf16 v[18:21], v[174:177], v[204:207], 0
	v_mfma_f32_16x16x32_bf16 v[18:21], v[170:173], v[200:203], v[18:21]
	v_mfma_f32_16x16x32_bf16 v[2:5], v[170:173], v[208:211], 0
	v_mfma_f32_16x16x32_bf16 v[2:5], v[174:177], v[212:215], v[2:5]
	v_mfma_f32_16x16x32_bf16 v[10:13], v[166:169], v[212:215], 0
	v_mfma_f32_16x16x32_bf16 v[10:13], v[162:165], v[208:211], v[10:13]
	s_barrier
	s_setprio 0
	s_add_i32 s0, 0, 0x18000
	v_add_u32_e32 v145, s0, v143
	s_add_i32 s1, 0, 0x1c000
	ds_read_b128 v[146:149], v145
	ds_read_b128 v[150:153], v145 offset:1024
	ds_read_b128 v[154:157], v145 offset:2048
	ds_read_b128 v[158:161], v145 offset:3072
	v_add_u32_e32 v145, s1, v143
	ds_read_b128 v[162:165], v145
	ds_read_b128 v[166:169], v145 offset:1024
	ds_read_b128 v[170:173], v145 offset:2048
	ds_read_b128 v[174:177], v145 offset:3072
	s_add_u32 s26, s26, 0x80000
	s_addc_u32 s27, s27, 0
	s_mov_b32 m0, s37
	ds_read_b128 v[178:181], v144 offset:32768
	ds_read_b128 v[182:185], v144 offset:33792
	ds_read_b128 v[192:195], v144 offset:34816
	ds_read_b128 v[196:199], v144 offset:35840
	ds_read_b128 v[200:203], v144 offset:36864
	ds_read_b128 v[204:207], v144 offset:37888
	ds_read_b128 v[208:211], v144 offset:38912
	ds_read_b128 v[212:215], v144 offset:39936
	global_load_lds_dwordx4 v134, s[26:27]
	s_mov_b32 m0, s38
	s_nop 0
	global_load_lds_dwordx4 v132, s[26:27]
	s_waitcnt vmcnt(8)
	s_waitcnt lgkmcnt(0)
	s_setprio 1
	s_barrier

	v_mfma_f32_16x16x32_bf16 v[126:129], v[146:149], v[178:181], v[126:129]
	v_mfma_f32_16x16x32_bf16 v[126:129], v[150:153], v[182:185], v[126:129]
	v_mfma_f32_16x16x32_bf16 v[118:121], v[158:161], v[182:185], v[118:121]
	v_mfma_f32_16x16x32_bf16 v[118:121], v[154:157], v[178:181], v[118:121]
	v_mfma_f32_16x16x32_bf16 v[102:105], v[154:157], v[192:195], v[102:105]
	v_mfma_f32_16x16x32_bf16 v[102:105], v[158:161], v[196:199], v[102:105]
	v_mfma_f32_16x16x32_bf16 v[110:113], v[150:153], v[196:199], v[110:113]
	v_mfma_f32_16x16x32_bf16 v[110:113], v[146:149], v[192:195], v[110:113]
	v_mfma_f32_16x16x32_bf16 v[94:97], v[146:149], v[200:203], v[94:97]
	v_mfma_f32_16x16x32_bf16 v[94:97], v[150:153], v[204:207], v[94:97]
	v_mfma_f32_16x16x32_bf16 v[86:89], v[158:161], v[204:207], v[86:89]
	v_mfma_f32_16x16x32_bf16 v[86:89], v[154:157], v[200:203], v[86:89]
	v_mfma_f32_16x16x32_bf16 v[70:73], v[154:157], v[208:211], v[70:73]
	v_mfma_f32_16x16x32_bf16 v[70:73], v[158:161], v[212:215], v[70:73]
	v_mfma_f32_16x16x32_bf16 v[78:81], v[150:153], v[212:215], v[78:81]
	v_mfma_f32_16x16x32_bf16 v[78:81], v[146:149], v[208:211], v[78:81]


	v_mfma_f32_16x16x32_bf16 v[122:125], v[162:165], v[178:181], v[122:125]
	v_mfma_f32_16x16x32_bf16 v[122:125], v[166:169], v[182:185], v[122:125]
	v_mfma_f32_16x16x32_bf16 v[114:117], v[174:177], v[182:185], v[114:117]
	v_mfma_f32_16x16x32_bf16 v[114:117], v[170:173], v[178:181], v[114:117]
	v_mfma_f32_16x16x32_bf16 v[98:101], v[170:173], v[192:195], v[98:101]
	v_mfma_f32_16x16x32_bf16 v[98:101], v[174:177], v[196:199], v[98:101]
	v_mfma_f32_16x16x32_bf16 v[106:109], v[166:169], v[196:199], v[106:109]
	v_mfma_f32_16x16x32_bf16 v[106:109], v[162:165], v[192:195], v[106:109]
	v_mfma_f32_16x16x32_bf16 v[90:93], v[162:165], v[200:203], v[90:93]
	v_mfma_f32_16x16x32_bf16 v[90:93], v[166:169], v[204:207], v[90:93]
	v_mfma_f32_16x16x32_bf16 v[82:85], v[174:177], v[204:207], v[82:85]
	v_mfma_f32_16x16x32_bf16 v[82:85], v[170:173], v[200:203], v[82:85]
	v_mfma_f32_16x16x32_bf16 v[66:69], v[170:173], v[208:211], v[66:69]
	v_mfma_f32_16x16x32_bf16 v[66:69], v[174:177], v[212:215], v[66:69]
	v_mfma_f32_16x16x32_bf16 v[74:77], v[166:169], v[212:215], v[74:77]
	v_mfma_f32_16x16x32_bf16 v[74:77], v[162:165], v[208:211], v[74:77]
	s_barrier
	s_setprio 0
	s_add_i32 s0, s0, s31
	s_mov_b32 m0, s0
	ds_read_b128 v[178:181], v144 offset:49152
	ds_read_b128 v[182:185], v144 offset:50176
	ds_read_b128 v[192:195], v144 offset:51200
	ds_read_b128 v[196:199], v144 offset:52224
	ds_read_b128 v[200:203], v144 offset:53248
	ds_read_b128 v[204:207], v144 offset:54272
	ds_read_b128 v[208:211], v144 offset:55296
	ds_read_b128 v[212:215], v144 offset:56320
	s_add_u32 s100, s24, 0x80
	s_addc_u32 s101, s25, 0
	global_load_lds_dwordx4 v186, s[100:101]
	s_add_i32 m0, s0, 0x2000
	s_add_u32 s24, s24, 0x80080
	s_addc_u32 s25, s25, 0
	s_add_i32 s0, s1, s31
	s_add_u32 s100, s24, 0xfff80000
	s_addc_u32 s101, s25, -1
	global_load_lds_dwordx4 v130, s[100:101]
	s_mov_b32 m0, s0
	s_nop 0
	global_load_lds_dwordx4 v186, s[24:25]
	s_add_i32 m0, s0, 0x2000
	s_nop 0
	global_load_lds_dwordx4 v130, s[24:25]
	s_mov_b32 m0, s39
	s_nop 0
	s_add_u32 s100, s26, 0xfff80080
	s_addc_u32 s101, s27, -1
	global_load_lds_dwordx4 v134, s[100:101]
	s_mov_b32 m0, s40
	s_nop 0
	s_add_u32 s100, s26, 0xfff80080
	s_addc_u32 s101, s27, -1
	global_load_lds_dwordx4 v132, s[100:101]
	s_waitcnt vmcnt(8)
	s_waitcnt lgkmcnt(0)
	s_setprio 1
	s_barrier

	v_mfma_f32_16x16x32_bf16 v[62:65], v[146:149], v[178:181], v[62:65]
	v_mfma_f32_16x16x32_bf16 v[62:65], v[150:153], v[182:185], v[62:65]
	v_mfma_f32_16x16x32_bf16 v[54:57], v[158:161], v[182:185], v[54:57]
	v_mfma_f32_16x16x32_bf16 v[54:57], v[154:157], v[178:181], v[54:57]
	v_mfma_f32_16x16x32_bf16 v[38:41], v[154:157], v[192:195], v[38:41]
	v_mfma_f32_16x16x32_bf16 v[38:41], v[158:161], v[196:199], v[38:41]
	v_mfma_f32_16x16x32_bf16 v[46:49], v[150:153], v[196:199], v[46:49]
	v_mfma_f32_16x16x32_bf16 v[46:49], v[146:149], v[192:195], v[46:49]
	v_mfma_f32_16x16x32_bf16 v[30:33], v[146:149], v[200:203], v[30:33]
	v_mfma_f32_16x16x32_bf16 v[30:33], v[150:153], v[204:207], v[30:33]
	v_mfma_f32_16x16x32_bf16 v[22:25], v[158:161], v[204:207], v[22:25]
	v_mfma_f32_16x16x32_bf16 v[22:25], v[154:157], v[200:203], v[22:25]
	v_mfma_f32_16x16x32_bf16 v[6:9], v[154:157], v[208:211], v[6:9]
	v_mfma_f32_16x16x32_bf16 v[6:9], v[158:161], v[212:215], v[6:9]
	v_mfma_f32_16x16x32_bf16 v[14:17], v[150:153], v[212:215], v[14:17]
	v_mfma_f32_16x16x32_bf16 v[14:17], v[146:149], v[208:211], v[14:17]


	v_mfma_f32_16x16x32_bf16 v[58:61], v[162:165], v[178:181], v[58:61]
	v_mfma_f32_16x16x32_bf16 v[58:61], v[166:169], v[182:185], v[58:61]
	v_mfma_f32_16x16x32_bf16 v[50:53], v[174:177], v[182:185], v[50:53]
	v_mfma_f32_16x16x32_bf16 v[50:53], v[170:173], v[178:181], v[50:53]
	v_mfma_f32_16x16x32_bf16 v[34:37], v[170:173], v[192:195], v[34:37]
	v_mfma_f32_16x16x32_bf16 v[34:37], v[174:177], v[196:199], v[34:37]
	v_mfma_f32_16x16x32_bf16 v[42:45], v[166:169], v[196:199], v[42:45]
	v_mfma_f32_16x16x32_bf16 v[42:45], v[162:165], v[192:195], v[42:45]
	v_mfma_f32_16x16x32_bf16 v[26:29], v[162:165], v[200:203], v[26:29]
	v_mfma_f32_16x16x32_bf16 v[26:29], v[166:169], v[204:207], v[26:29]
	v_mfma_f32_16x16x32_bf16 v[18:21], v[174:177], v[204:207], v[18:21]
	v_mfma_f32_16x16x32_bf16 v[18:21], v[170:173], v[200:203], v[18:21]
	v_mfma_f32_16x16x32_bf16 v[2:5], v[170:173], v[208:211], v[2:5]
	v_mfma_f32_16x16x32_bf16 v[2:5], v[174:177], v[212:215], v[2:5]
	v_mfma_f32_16x16x32_bf16 v[10:13], v[166:169], v[212:215], v[10:13]
	v_mfma_f32_16x16x32_bf16 v[10:13], v[162:165], v[208:211], v[10:13]
	s_barrier
	s_setprio 0
	s_add_i32 s50, s50, 2
	s_add_u32 s22, s22, 0x100
	s_addc_u32 s23, s23, 0
	s_add_u32 s48, s48, 0x100
	s_addc_u32 s49, s49, 0
	s_cmp_gt_u32 s50, 29
	s_cbranch_scc0 .LBB0_159

.LBB0_242:
	s_add_u32 s49, s22, 0x100
	s_addc_u32 s50, s23, 0
	s_mov_b32 s51, -2
	s_add_u32 s22, s20, 0x100
	s_addc_u32 s23, s21, 0
	s_add_i32 s0, 0, 0x10000
	s_cmpk_eq_i32 s51, 0x54
	s_cselect_b32 s27, s7, s23
	s_cselect_b32 s26, s6, s22
	s_cselect_b32 s25, s19, s50
	s_cselect_b32 s24, s18, s49
	s_add_i32 s1, 0, 0x14000
	v_add_u32_e32 v126, s0, v237
	v_add_u32_e32 v158, s1, v237
	ds_read_b128 v[90:93], v126
	ds_read_b128 v[102:105], v126 offset:1024
	ds_read_b128 v[114:117], v126 offset:2048
	ds_read_b128 v[126:129], v126 offset:3072
	ds_read_b128 v[138:141], v158
	ds_read_b128 v[142:145], v158 offset:1024
	ds_read_b128 v[154:157], v158 offset:2048
	ds_read_b128 v[158:161], v158 offset:3072
	v_lshl_add_u64 v[210:211], s[20:21], 0, v[198:199]
	s_add_i32 m0, s34, 0xc000
	ds_read_b128 v[162:165], v238
	ds_read_b128 v[166:169], v238 offset:1024
	ds_read_b128 v[170:173], v238 offset:2048
	ds_read_b128 v[174:177], v238 offset:3072
	ds_read_b128 v[178:181], v238 offset:4096
	ds_read_b128 v[182:185], v238 offset:5120
	ds_read_b128 v[202:205], v238 offset:6144
	ds_read_b128 v[206:209], v238 offset:7168
	global_load_lds_dwordx4 v[210:211], off
	v_lshl_add_u64 v[210:211], s[20:21], 0, v[200:201]
	s_add_i32 m0, s34, 0xe000
	s_nop 0
	global_load_lds_dwordx4 v[210:211], off
	s_waitcnt vmcnt(8)
	s_waitcnt lgkmcnt(0)
	s_setprio 1
	s_barrier

	v_mfma_f32_16x16x32_bf16 v[150:153], v[90:93], v[162:165], 0
	v_mfma_f32_16x16x32_bf16 v[150:153], v[102:105], v[166:169], v[150:153]
	v_mfma_f32_16x16x32_bf16 v[146:149], v[126:129], v[166:169], 0
	v_mfma_f32_16x16x32_bf16 v[146:149], v[114:117], v[162:165], v[146:149]
	v_mfma_f32_16x16x32_bf16 v[118:121], v[114:117], v[170:173], 0
	v_mfma_f32_16x16x32_bf16 v[118:121], v[126:129], v[174:177], v[118:121]
	v_mfma_f32_16x16x32_bf16 v[122:125], v[102:105], v[174:177], 0
	v_mfma_f32_16x16x32_bf16 v[122:125], v[90:93], v[170:173], v[122:125]
	v_mfma_f32_16x16x32_bf16 v[98:101], v[90:93], v[178:181], 0
	v_mfma_f32_16x16x32_bf16 v[98:101], v[102:105], v[182:185], v[98:101]
	v_mfma_f32_16x16x32_bf16 v[94:97], v[126:129], v[182:185], 0
	v_mfma_f32_16x16x32_bf16 v[94:97], v[114:117], v[178:181], v[94:97]
	v_mfma_f32_16x16x32_bf16 v[74:77], v[114:117], v[202:205], 0
	v_mfma_f32_16x16x32_bf16 v[74:77], v[126:129], v[206:209], v[74:77]
	v_mfma_f32_16x16x32_bf16 v[78:81], v[102:105], v[206:209], 0
	v_mfma_f32_16x16x32_bf16 v[78:81], v[90:93], v[202:205], v[78:81]


	v_mfma_f32_16x16x32_bf16 v[134:137], v[138:141], v[162:165], 0
	v_mfma_f32_16x16x32_bf16 v[134:137], v[142:145], v[166:169], v[134:137]
	v_mfma_f32_16x16x32_bf16 v[130:133], v[158:161], v[166:169], 0
	v_mfma_f32_16x16x32_bf16 v[130:133], v[154:157], v[162:165], v[130:133]
	v_mfma_f32_16x16x32_bf16 v[106:109], v[154:157], v[170:173], 0
	v_mfma_f32_16x16x32_bf16 v[106:109], v[158:161], v[174:177], v[106:109]
	v_mfma_f32_16x16x32_bf16 v[110:113], v[142:145], v[174:177], 0
	v_mfma_f32_16x16x32_bf16 v[110:113], v[138:141], v[170:173], v[110:113]
	v_mfma_f32_16x16x32_bf16 v[86:89], v[138:141], v[178:181], 0
	v_mfma_f32_16x16x32_bf16 v[86:89], v[142:145], v[182:185], v[86:89]
	v_mfma_f32_16x16x32_bf16 v[82:85], v[158:161], v[182:185], 0
	v_mfma_f32_16x16x32_bf16 v[82:85], v[154:157], v[178:181], v[82:85]
	v_mfma_f32_16x16x32_bf16 v[66:69], v[154:157], v[202:205], 0
	v_mfma_f32_16x16x32_bf16 v[66:69], v[158:161], v[206:209], v[66:69]
	v_mfma_f32_16x16x32_bf16 v[70:73], v[142:145], v[206:209], 0
	v_mfma_f32_16x16x32_bf16 v[70:73], v[138:141], v[202:205], v[70:73]
	s_barrier
	s_setprio 0
	s_add_i32 s0, s0, s31
	v_lshl_add_u64 v[210:211], s[24:25], 0, v[186:187]
	s_mov_b32 m0, s0
	ds_read_b128 v[162:165], v238 offset:16384
	ds_read_b128 v[166:169], v238 offset:17408
	ds_read_b128 v[170:173], v238 offset:18432
	ds_read_b128 v[174:177], v238 offset:19456
	ds_read_b128 v[178:181], v238 offset:20480
	ds_read_b128 v[182:185], v238 offset:21504
	ds_read_b128 v[202:205], v238 offset:22528
	ds_read_b128 v[206:209], v238 offset:23552
	global_load_lds_dwordx4 v[210:211], off
	s_add_i32 m0, s0, 0x2000
	s_add_u32 s20, s24, 0x160000
	v_lshl_add_u64 v[212:213], s[24:25], 0, v[196:197]
	s_addc_u32 s21, s25, 0
	s_add_i32 s0, s1, s31
	global_load_lds_dwordx4 v[212:213], off
	v_lshl_add_u64 v[214:215], s[20:21], 0, v[186:187]
	s_mov_b32 m0, s0
	v_lshl_add_u64 v[216:217], s[26:27], 0, v[194:195]
	global_load_lds_dwordx4 v[214:215], off
	v_lshl_add_u64 v[214:215], s[20:21], 0, v[196:197]
	s_add_i32 m0, s0, 0x2000
	s_nop 0
	global_load_lds_dwordx4 v[214:215], off
	v_lshl_add_u64 v[214:215], s[26:27], 0, v[192:193]
	s_mov_b32 m0, s34
	s_nop 0
	global_load_lds_dwordx4 v[214:215], off
	s_mov_b32 m0, s35
	s_nop 0
	global_load_lds_dwordx4 v[216:217], off
	s_waitcnt vmcnt(8)
	s_waitcnt lgkmcnt(0)
	s_setprio 1
	s_barrier

	v_mfma_f32_16x16x32_bf16 v[62:65], v[90:93], v[162:165], 0
	v_mfma_f32_16x16x32_bf16 v[62:65], v[102:105], v[166:169], v[62:65]
	v_mfma_f32_16x16x32_bf16 v[58:61], v[126:129], v[166:169], 0
	v_mfma_f32_16x16x32_bf16 v[58:61], v[114:117], v[162:165], v[58:61]
	v_mfma_f32_16x16x32_bf16 v[42:45], v[114:117], v[170:173], 0
	v_mfma_f32_16x16x32_bf16 v[42:45], v[126:129], v[174:177], v[42:45]
	v_mfma_f32_16x16x32_bf16 v[46:49], v[102:105], v[174:177], 0
	v_mfma_f32_16x16x32_bf16 v[46:49], v[90:93], v[170:173], v[46:49]
	v_mfma_f32_16x16x32_bf16 v[30:33], v[90:93], v[178:181], 0
	v_mfma_f32_16x16x32_bf16 v[30:33], v[102:105], v[182:185], v[30:33]
	v_mfma_f32_16x16x32_bf16 v[26:29], v[126:129], v[182:185], 0
	v_mfma_f32_16x16x32_bf16 v[26:29], v[114:117], v[178:181], v[26:29]
	v_mfma_f32_16x16x32_bf16 v[10:13], v[114:117], v[202:205], 0
	v_mfma_f32_16x16x32_bf16 v[10:13], v[126:129], v[206:209], v[10:13]
	v_mfma_f32_16x16x32_bf16 v[14:17], v[102:105], v[206:209], 0
	v_mfma_f32_16x16x32_bf16 v[14:17], v[90:93], v[202:205], v[14:17]


	v_mfma_f32_16x16x32_bf16 v[54:57], v[138:141], v[162:165], 0
	v_mfma_f32_16x16x32_bf16 v[54:57], v[142:145], v[166:169], v[54:57]
	v_mfma_f32_16x16x32_bf16 v[50:53], v[158:161], v[166:169], 0
	v_mfma_f32_16x16x32_bf16 v[50:53], v[154:157], v[162:165], v[50:53]
	v_mfma_f32_16x16x32_bf16 v[34:37], v[154:157], v[170:173], 0
	v_mfma_f32_16x16x32_bf16 v[34:37], v[158:161], v[174:177], v[34:37]
	v_mfma_f32_16x16x32_bf16 v[38:41], v[142:145], v[174:177], 0
	v_mfma_f32_16x16x32_bf16 v[38:41], v[138:141], v[170:173], v[38:41]
	v_mfma_f32_16x16x32_bf16 v[22:25], v[138:141], v[178:181], 0
	v_mfma_f32_16x16x32_bf16 v[22:25], v[142:145], v[182:185], v[22:25]
	v_mfma_f32_16x16x32_bf16 v[18:21], v[158:161], v[182:185], 0
	v_mfma_f32_16x16x32_bf16 v[18:21], v[154:157], v[178:181], v[18:21]
	v_mfma_f32_16x16x32_bf16 v[2:5], v[154:157], v[202:205], 0
	v_mfma_f32_16x16x32_bf16 v[2:5], v[158:161], v[206:209], v[2:5]
	v_mfma_f32_16x16x32_bf16 v[6:9], v[142:145], v[206:209], 0
	v_mfma_f32_16x16x32_bf16 v[6:9], v[138:141], v[202:205], v[6:9]
	s_barrier
	s_setprio 0
	s_add_i32 s0, 0, 0x18000
	s_add_i32 s1, 0, 0x1c000
	v_add_u32_e32 v126, s0, v237
	v_add_u32_e32 v158, s1, v237
	ds_read_b128 v[90:93], v126
	ds_read_b128 v[102:105], v126 offset:1024
	ds_read_b128 v[114:117], v126 offset:2048
	ds_read_b128 v[126:129], v126 offset:3072
	ds_read_b128 v[138:141], v158
	ds_read_b128 v[142:145], v158 offset:1024
	ds_read_b128 v[154:157], v158 offset:2048
	ds_read_b128 v[158:161], v158 offset:3072
	s_add_u32 s20, s26, 0x160000
	s_addc_u32 s21, s27, 0
	s_mov_b32 m0, s36
	v_lshl_add_u64 v[218:219], s[20:21], 0, v[192:193]
	ds_read_b128 v[162:165], v238 offset:32768
	ds_read_b128 v[166:169], v238 offset:33792
	ds_read_b128 v[170:173], v238 offset:34816
	ds_read_b128 v[174:177], v238 offset:35840
	ds_read_b128 v[178:181], v238 offset:36864
	ds_read_b128 v[182:185], v238 offset:37888
	ds_read_b128 v[202:205], v238 offset:38912
	ds_read_b128 v[206:209], v238 offset:39936
	global_load_lds_dwordx4 v[218:219], off
	v_lshl_add_u64 v[218:219], s[20:21], 0, v[194:195]
	s_mov_b32 m0, s37
	s_nop 0
	global_load_lds_dwordx4 v[218:219], off
	s_waitcnt vmcnt(8)
	s_waitcnt lgkmcnt(0)
	s_setprio 1
	s_barrier

	v_mfma_f32_16x16x32_bf16 v[150:153], v[90:93], v[162:165], v[150:153]
	v_mfma_f32_16x16x32_bf16 v[150:153], v[102:105], v[166:169], v[150:153]
	v_mfma_f32_16x16x32_bf16 v[146:149], v[126:129], v[166:169], v[146:149]
	v_mfma_f32_16x16x32_bf16 v[146:149], v[114:117], v[162:165], v[146:149]
	v_mfma_f32_16x16x32_bf16 v[118:121], v[114:117], v[170:173], v[118:121]
	v_mfma_f32_16x16x32_bf16 v[118:121], v[126:129], v[174:177], v[118:121]
	v_mfma_f32_16x16x32_bf16 v[122:125], v[102:105], v[174:177], v[122:125]
	v_mfma_f32_16x16x32_bf16 v[122:125], v[90:93], v[170:173], v[122:125]
	v_mfma_f32_16x16x32_bf16 v[98:101], v[90:93], v[178:181], v[98:101]
	v_mfma_f32_16x16x32_bf16 v[98:101], v[102:105], v[182:185], v[98:101]
	v_mfma_f32_16x16x32_bf16 v[94:97], v[126:129], v[182:185], v[94:97]
	v_mfma_f32_16x16x32_bf16 v[94:97], v[114:117], v[178:181], v[94:97]
	v_mfma_f32_16x16x32_bf16 v[74:77], v[114:117], v[202:205], v[74:77]
	v_mfma_f32_16x16x32_bf16 v[74:77], v[126:129], v[206:209], v[74:77]
	v_mfma_f32_16x16x32_bf16 v[78:81], v[102:105], v[206:209], v[78:81]
	v_mfma_f32_16x16x32_bf16 v[78:81], v[90:93], v[202:205], v[78:81]


	v_mfma_f32_16x16x32_bf16 v[134:137], v[138:141], v[162:165], v[134:137]
	v_mfma_f32_16x16x32_bf16 v[134:137], v[142:145], v[166:169], v[134:137]
	v_mfma_f32_16x16x32_bf16 v[130:133], v[158:161], v[166:169], v[130:133]
	v_mfma_f32_16x16x32_bf16 v[130:133], v[154:157], v[162:165], v[130:133]
	v_mfma_f32_16x16x32_bf16 v[106:109], v[154:157], v[170:173], v[106:109]
	v_mfma_f32_16x16x32_bf16 v[106:109], v[158:161], v[174:177], v[106:109]
	v_mfma_f32_16x16x32_bf16 v[110:113], v[142:145], v[174:177], v[110:113]
	v_mfma_f32_16x16x32_bf16 v[110:113], v[138:141], v[170:173], v[110:113]
	v_mfma_f32_16x16x32_bf16 v[86:89], v[138:141], v[178:181], v[86:89]
	v_mfma_f32_16x16x32_bf16 v[86:89], v[142:145], v[182:185], v[86:89]
	v_mfma_f32_16x16x32_bf16 v[82:85], v[158:161], v[182:185], v[82:85]
	v_mfma_f32_16x16x32_bf16 v[82:85], v[154:157], v[178:181], v[82:85]
	v_mfma_f32_16x16x32_bf16 v[66:69], v[154:157], v[202:205], v[66:69]
	v_mfma_f32_16x16x32_bf16 v[66:69], v[158:161], v[206:209], v[66:69]
	v_mfma_f32_16x16x32_bf16 v[70:73], v[142:145], v[206:209], v[70:73]
	v_mfma_f32_16x16x32_bf16 v[70:73], v[138:141], v[202:205], v[70:73]
	s_barrier
	s_setprio 0
	s_add_i32 s0, s0, s31
	v_lshl_add_u64 v[210:211], v[210:211], 0, s[84:85]
	s_mov_b32 m0, s0
	ds_read_b128 v[162:165], v238 offset:49152
	ds_read_b128 v[166:169], v238 offset:50176
	ds_read_b128 v[170:173], v238 offset:51200
	ds_read_b128 v[174:177], v238 offset:52224
	ds_read_b128 v[178:181], v238 offset:53248
	ds_read_b128 v[182:185], v238 offset:54272
	ds_read_b128 v[202:205], v238 offset:55296
	ds_read_b128 v[206:209], v238 offset:56320
	global_load_lds_dwordx4 v[210:211], off
	s_add_i32 m0, s0, 0x2000
	s_add_u32 s20, s24, 0x160080
	v_lshl_add_u64 v[210:211], v[212:213], 0, s[84:85]
	s_addc_u32 s21, s25, 0
	s_add_i32 s0, s1, s31
	global_load_lds_dwordx4 v[210:211], off
	v_lshl_add_u64 v[210:211], s[20:21], 0, v[186:187]
	s_mov_b32 m0, s0
	s_nop 0
	global_load_lds_dwordx4 v[210:211], off
	v_lshl_add_u64 v[210:211], s[20:21], 0, v[196:197]
	s_add_i32 m0, s0, 0x2000
	s_nop 0
	global_load_lds_dwordx4 v[210:211], off
	v_lshl_add_u64 v[210:211], v[214:215], 0, s[84:85]
	s_mov_b32 m0, s41
	s_nop 0
	global_load_lds_dwordx4 v[210:211], off
	v_lshl_add_u64 v[210:211], v[216:217], 0, s[84:85]
	s_mov_b32 m0, s42
	s_nop 0
	global_load_lds_dwordx4 v[210:211], off
	s_waitcnt vmcnt(8)
	s_waitcnt lgkmcnt(0)
	s_setprio 1
	s_barrier

	v_mfma_f32_16x16x32_bf16 v[62:65], v[90:93], v[162:165], v[62:65]
	v_mfma_f32_16x16x32_bf16 v[62:65], v[102:105], v[166:169], v[62:65]
	v_mfma_f32_16x16x32_bf16 v[58:61], v[126:129], v[166:169], v[58:61]
	v_mfma_f32_16x16x32_bf16 v[58:61], v[114:117], v[162:165], v[58:61]
	v_mfma_f32_16x16x32_bf16 v[42:45], v[114:117], v[170:173], v[42:45]
	v_mfma_f32_16x16x32_bf16 v[42:45], v[126:129], v[174:177], v[42:45]
	v_mfma_f32_16x16x32_bf16 v[46:49], v[102:105], v[174:177], v[46:49]
	v_mfma_f32_16x16x32_bf16 v[46:49], v[90:93], v[170:173], v[46:49]
	v_mfma_f32_16x16x32_bf16 v[30:33], v[90:93], v[178:181], v[30:33]
	v_mfma_f32_16x16x32_bf16 v[30:33], v[102:105], v[182:185], v[30:33]
	v_mfma_f32_16x16x32_bf16 v[26:29], v[126:129], v[182:185], v[26:29]
	v_mfma_f32_16x16x32_bf16 v[26:29], v[114:117], v[178:181], v[26:29]
	v_mfma_f32_16x16x32_bf16 v[10:13], v[114:117], v[202:205], v[10:13]
	v_mfma_f32_16x16x32_bf16 v[10:13], v[126:129], v[206:209], v[10:13]
	v_mfma_f32_16x16x32_bf16 v[14:17], v[102:105], v[206:209], v[14:17]
	v_mfma_f32_16x16x32_bf16 v[14:17], v[90:93], v[202:205], v[14:17]


	v_mfma_f32_16x16x32_bf16 v[54:57], v[138:141], v[162:165], v[54:57]
	v_mfma_f32_16x16x32_bf16 v[54:57], v[142:145], v[166:169], v[54:57]
	v_mfma_f32_16x16x32_bf16 v[50:53], v[158:161], v[166:169], v[50:53]
	v_mfma_f32_16x16x32_bf16 v[50:53], v[154:157], v[162:165], v[50:53]
	v_mfma_f32_16x16x32_bf16 v[34:37], v[154:157], v[170:173], v[34:37]
	v_mfma_f32_16x16x32_bf16 v[34:37], v[158:161], v[174:177], v[34:37]
	v_mfma_f32_16x16x32_bf16 v[38:41], v[142:145], v[174:177], v[38:41]
	v_mfma_f32_16x16x32_bf16 v[38:41], v[138:141], v[170:173], v[38:41]
	v_mfma_f32_16x16x32_bf16 v[22:25], v[138:141], v[178:181], v[22:25]
	v_mfma_f32_16x16x32_bf16 v[22:25], v[142:145], v[182:185], v[22:25]
	v_mfma_f32_16x16x32_bf16 v[18:21], v[158:161], v[182:185], v[18:21]
	v_mfma_f32_16x16x32_bf16 v[18:21], v[154:157], v[178:181], v[18:21]
	v_mfma_f32_16x16x32_bf16 v[2:5], v[154:157], v[202:205], v[2:5]
	v_mfma_f32_16x16x32_bf16 v[2:5], v[158:161], v[206:209], v[2:5]
	v_mfma_f32_16x16x32_bf16 v[6:9], v[142:145], v[206:209], v[6:9]
	v_mfma_f32_16x16x32_bf16 v[6:9], v[138:141], v[202:205], v[6:9]
	s_barrier
	s_setprio 0
	s_add_i32 s51, s51, 2
	s_add_u32 s49, s49, 0x100
	s_addc_u32 s50, s50, 0
	s_cmpk_gt_u32 s51, 0x55
	s_mov_b64 s[20:21], s[22:23]
	s_cbranch_scc0 .LBB0_243

.LBB0_442:
	s_ashr_i32 s19, s18, 31
	s_lshl_b64 s[20:21], s[18:19], 20
	s_add_u32 s20, s35, s20
	s_addc_u32 s21, s36, s21
	s_and_b64 s[22:23], s[4:5], exec
	s_cselect_b32 s19, s21, s27
	s_cselect_b32 s51, s20, s26
	s_ashr_i32 s17, s16, 31
	s_lshl_b64 s[22:23], s[16:17], 20
	s_add_u32 s22, s37, s22
	s_addc_u32 s23, s38, s23
	s_and_b64 s[30:31], s[4:5], exec
	s_cselect_b32 s17, s23, s29
	s_cselect_b32 s52, s22, s28
	s_add_u32 s26, s26, 0x80080
	s_addc_u32 s27, s27, 0
	s_add_u32 s53, s28, 0x100
	s_addc_u32 s54, s29, 0
	s_mov_b32 s55, -2
	s_add_u32 s0, s26, 0xfff80080
	s_addc_u32 s1, s27, -1
	s_add_i32 s56, 0, 0x10000
	s_cmp_eq_u32 s55, 28
	s_cselect_b32 s31, s19, s1
	s_cselect_b32 s30, s51, s0
	v_add_u32_e32 v140, s56, v144
	s_cselect_b32 s29, s17, s54
	s_cselect_b32 s28, s52, s53
	s_add_i32 s0, 0, 0x14000
	ds_read_b128 v[146:149], v140
	ds_read_b128 v[150:153], v140 offset:1024
	ds_read_b128 v[154:157], v140 offset:2048
	ds_read_b128 v[158:161], v140 offset:3072
	v_add_u32_e32 v140, s0, v144
	ds_read_b128 v[162:165], v140
	ds_read_b128 v[166:169], v140 offset:1024
	ds_read_b128 v[170:173], v140 offset:2048
	ds_read_b128 v[174:177], v140 offset:3072
	s_add_i32 m0, s25, 0xc000
	ds_read_b128 v[178:181], v145
	ds_read_b128 v[182:185], v145 offset:1024
	ds_read_b128 v[192:195], v145 offset:2048
	ds_read_b128 v[196:199], v145 offset:3072
	ds_read_b128 v[200:203], v145 offset:4096
	ds_read_b128 v[204:207], v145 offset:5120
	ds_read_b128 v[208:211], v145 offset:6144
	ds_read_b128 v[212:215], v145 offset:7168
	global_load_lds_dwordx4 v136, s[26:27]
	s_add_i32 m0, s25, 0xe000
	s_nop 0
	global_load_lds_dwordx4 v138, s[26:27]
	s_waitcnt vmcnt(8)
	s_waitcnt lgkmcnt(0)
	s_setprio 1
	s_barrier

	v_mfma_f32_16x16x32_bf16 v[126:129], v[146:149], v[178:181], 0
	v_mfma_f32_16x16x32_bf16 v[126:129], v[150:153], v[182:185], v[126:129]
	v_mfma_f32_16x16x32_bf16 v[122:125], v[158:161], v[182:185], 0
	v_mfma_f32_16x16x32_bf16 v[122:125], v[154:157], v[178:181], v[122:125]
	v_mfma_f32_16x16x32_bf16 v[106:109], v[154:157], v[192:195], 0
	v_mfma_f32_16x16x32_bf16 v[106:109], v[158:161], v[196:199], v[106:109]
	v_mfma_f32_16x16x32_bf16 v[114:117], v[150:153], v[196:199], 0
	v_mfma_f32_16x16x32_bf16 v[114:117], v[146:149], v[192:195], v[114:117]
	v_mfma_f32_16x16x32_bf16 v[98:101], v[146:149], v[200:203], 0
	v_mfma_f32_16x16x32_bf16 v[98:101], v[150:153], v[204:207], v[98:101]
	v_mfma_f32_16x16x32_bf16 v[90:93], v[158:161], v[204:207], 0
	v_mfma_f32_16x16x32_bf16 v[90:93], v[154:157], v[200:203], v[90:93]
	v_mfma_f32_16x16x32_bf16 v[74:77], v[154:157], v[208:211], 0
	v_mfma_f32_16x16x32_bf16 v[74:77], v[158:161], v[212:215], v[74:77]
	v_mfma_f32_16x16x32_bf16 v[82:85], v[150:153], v[212:215], 0
	v_mfma_f32_16x16x32_bf16 v[82:85], v[146:149], v[208:211], v[82:85]


	v_mfma_f32_16x16x32_bf16 v[118:121], v[162:165], v[178:181], 0
	v_mfma_f32_16x16x32_bf16 v[118:121], v[166:169], v[182:185], v[118:121]
	v_mfma_f32_16x16x32_bf16 v[110:113], v[174:177], v[182:185], 0
	v_mfma_f32_16x16x32_bf16 v[110:113], v[170:173], v[178:181], v[110:113]
	v_mfma_f32_16x16x32_bf16 v[94:97], v[170:173], v[192:195], 0
	v_mfma_f32_16x16x32_bf16 v[94:97], v[174:177], v[196:199], v[94:97]
	v_mfma_f32_16x16x32_bf16 v[102:105], v[166:169], v[196:199], 0
	v_mfma_f32_16x16x32_bf16 v[102:105], v[162:165], v[192:195], v[102:105]
	v_mfma_f32_16x16x32_bf16 v[86:89], v[162:165], v[200:203], 0
	v_mfma_f32_16x16x32_bf16 v[86:89], v[166:169], v[204:207], v[86:89]
	v_mfma_f32_16x16x32_bf16 v[78:81], v[174:177], v[204:207], 0
	v_mfma_f32_16x16x32_bf16 v[78:81], v[170:173], v[200:203], v[78:81]
	v_mfma_f32_16x16x32_bf16 v[66:69], v[170:173], v[208:211], 0
	v_mfma_f32_16x16x32_bf16 v[66:69], v[174:177], v[212:215], v[66:69]
	v_mfma_f32_16x16x32_bf16 v[70:73], v[166:169], v[212:215], 0
	v_mfma_f32_16x16x32_bf16 v[70:73], v[162:165], v[208:211], v[70:73]
	s_barrier
	s_setprio 0
	s_add_i32 s1, s56, s39
	s_mov_b32 m0, s1
	ds_read_b128 v[178:181], v145 offset:16384
	ds_read_b128 v[182:185], v145 offset:17408
	ds_read_b128 v[192:195], v145 offset:18432
	ds_read_b128 v[196:199], v145 offset:19456
	ds_read_b128 v[200:203], v145 offset:20480
	ds_read_b128 v[204:207], v145 offset:21504
	ds_read_b128 v[208:211], v145 offset:22528
	ds_read_b128 v[212:215], v145 offset:23552
	global_load_lds_dwordx4 v186, s[28:29]
	s_add_i32 m0, s1, 0x2000
	s_add_u32 s56, s28, 0x80000
	s_addc_u32 s57, s29, 0
	s_add_i32 s0, s0, s39
	global_load_lds_dwordx4 v130, s[28:29]
	s_mov_b32 m0, s0
	s_nop 0
	global_load_lds_dwordx4 v186, s[56:57]
	s_add_i32 m0, s0, 0x2000
	s_nop 0
	global_load_lds_dwordx4 v130, s[56:57]
	s_mov_b32 m0, s25
	s_nop 0
	global_load_lds_dwordx4 v134, s[30:31]
	s_mov_b32 m0, s40
	s_nop 0
	global_load_lds_dwordx4 v132, s[30:31]
	s_waitcnt vmcnt(8)
	s_waitcnt lgkmcnt(0)
	s_setprio 1
	s_barrier

	v_mfma_f32_16x16x32_bf16 v[62:65], v[146:149], v[178:181], 0
	v_mfma_f32_16x16x32_bf16 v[62:65], v[150:153], v[182:185], v[62:65]
	v_mfma_f32_16x16x32_bf16 v[58:61], v[158:161], v[182:185], 0
	v_mfma_f32_16x16x32_bf16 v[58:61], v[154:157], v[178:181], v[58:61]
	v_mfma_f32_16x16x32_bf16 v[42:45], v[154:157], v[192:195], 0
	v_mfma_f32_16x16x32_bf16 v[42:45], v[158:161], v[196:199], v[42:45]
	v_mfma_f32_16x16x32_bf16 v[50:53], v[150:153], v[196:199], 0
	v_mfma_f32_16x16x32_bf16 v[50:53], v[146:149], v[192:195], v[50:53]
	v_mfma_f32_16x16x32_bf16 v[34:37], v[146:149], v[200:203], 0
	v_mfma_f32_16x16x32_bf16 v[34:37], v[150:153], v[204:207], v[34:37]
	v_mfma_f32_16x16x32_bf16 v[26:29], v[158:161], v[204:207], 0
	v_mfma_f32_16x16x32_bf16 v[26:29], v[154:157], v[200:203], v[26:29]
	v_mfma_f32_16x16x32_bf16 v[10:13], v[154:157], v[208:211], 0
	v_mfma_f32_16x16x32_bf16 v[10:13], v[158:161], v[212:215], v[10:13]
	v_mfma_f32_16x16x32_bf16 v[18:21], v[150:153], v[212:215], 0
	v_mfma_f32_16x16x32_bf16 v[18:21], v[146:149], v[208:211], v[18:21]


	v_mfma_f32_16x16x32_bf16 v[54:57], v[162:165], v[178:181], 0
	v_mfma_f32_16x16x32_bf16 v[54:57], v[166:169], v[182:185], v[54:57]
	v_mfma_f32_16x16x32_bf16 v[46:49], v[174:177], v[182:185], 0
	v_mfma_f32_16x16x32_bf16 v[46:49], v[170:173], v[178:181], v[46:49]
	v_mfma_f32_16x16x32_bf16 v[30:33], v[170:173], v[192:195], 0
	v_mfma_f32_16x16x32_bf16 v[30:33], v[174:177], v[196:199], v[30:33]
	v_mfma_f32_16x16x32_bf16 v[38:41], v[166:169], v[196:199], 0
	v_mfma_f32_16x16x32_bf16 v[38:41], v[162:165], v[192:195], v[38:41]
	v_mfma_f32_16x16x32_bf16 v[22:25], v[162:165], v[200:203], 0
	v_mfma_f32_16x16x32_bf16 v[22:25], v[166:169], v[204:207], v[22:25]
	v_mfma_f32_16x16x32_bf16 v[14:17], v[174:177], v[204:207], 0
	v_mfma_f32_16x16x32_bf16 v[14:17], v[170:173], v[200:203], v[14:17]
	v_mfma_f32_16x16x32_bf16 v[2:5], v[170:173], v[208:211], 0
	v_mfma_f32_16x16x32_bf16 v[2:5], v[174:177], v[212:215], v[2:5]
	v_mfma_f32_16x16x32_bf16 v[6:9], v[166:169], v[212:215], 0
	v_mfma_f32_16x16x32_bf16 v[6:9], v[162:165], v[208:211], v[6:9]
	s_barrier
	s_setprio 0
	s_add_i32 s0, 0, 0x18000
	s_add_i32 s1, 0, 0x1c000
	v_add_u32_e32 v158, s0, v144
	v_add_u32_e32 v174, s1, v144
	ds_read_b128 v[146:149], v158
	ds_read_b128 v[150:153], v158 offset:1024
	ds_read_b128 v[154:157], v158 offset:2048
	ds_read_b128 v[158:161], v158 offset:3072
	ds_read_b128 v[162:165], v174
	ds_read_b128 v[166:169], v174 offset:1024
	ds_read_b128 v[170:173], v174 offset:2048
	ds_read_b128 v[174:177], v174 offset:3072
	s_add_u32 s30, s30, 0x80000
	s_addc_u32 s31, s31, 0
	s_mov_b32 m0, s41
	ds_read_b128 v[178:181], v145 offset:32768
	ds_read_b128 v[182:185], v145 offset:33792
	ds_read_b128 v[192:195], v145 offset:34816
	ds_read_b128 v[196:199], v145 offset:35840
	ds_read_b128 v[200:203], v145 offset:36864
	ds_read_b128 v[204:207], v145 offset:37888
	ds_read_b128 v[208:211], v145 offset:38912
	ds_read_b128 v[212:215], v145 offset:39936
	global_load_lds_dwordx4 v134, s[30:31]
	s_mov_b32 m0, s42
	s_nop 0
	global_load_lds_dwordx4 v132, s[30:31]
	s_waitcnt vmcnt(8)
	s_waitcnt lgkmcnt(0)
	s_setprio 1
	s_barrier

	v_mfma_f32_16x16x32_bf16 v[126:129], v[146:149], v[178:181], v[126:129]
	v_mfma_f32_16x16x32_bf16 v[126:129], v[150:153], v[182:185], v[126:129]
	v_mfma_f32_16x16x32_bf16 v[122:125], v[158:161], v[182:185], v[122:125]
	v_mfma_f32_16x16x32_bf16 v[122:125], v[154:157], v[178:181], v[122:125]
	v_mfma_f32_16x16x32_bf16 v[106:109], v[154:157], v[192:195], v[106:109]
	v_mfma_f32_16x16x32_bf16 v[106:109], v[158:161], v[196:199], v[106:109]
	v_mfma_f32_16x16x32_bf16 v[114:117], v[150:153], v[196:199], v[114:117]
	v_mfma_f32_16x16x32_bf16 v[114:117], v[146:149], v[192:195], v[114:117]
	v_mfma_f32_16x16x32_bf16 v[98:101], v[146:149], v[200:203], v[98:101]
	v_mfma_f32_16x16x32_bf16 v[98:101], v[150:153], v[204:207], v[98:101]
	v_mfma_f32_16x16x32_bf16 v[90:93], v[158:161], v[204:207], v[90:93]
	v_mfma_f32_16x16x32_bf16 v[90:93], v[154:157], v[200:203], v[90:93]
	v_mfma_f32_16x16x32_bf16 v[74:77], v[154:157], v[208:211], v[74:77]
	v_mfma_f32_16x16x32_bf16 v[74:77], v[158:161], v[212:215], v[74:77]
	v_mfma_f32_16x16x32_bf16 v[82:85], v[150:153], v[212:215], v[82:85]
	v_mfma_f32_16x16x32_bf16 v[82:85], v[146:149], v[208:211], v[82:85]


	v_mfma_f32_16x16x32_bf16 v[118:121], v[162:165], v[178:181], v[118:121]
	v_mfma_f32_16x16x32_bf16 v[118:121], v[166:169], v[182:185], v[118:121]
	v_mfma_f32_16x16x32_bf16 v[110:113], v[174:177], v[182:185], v[110:113]
	v_mfma_f32_16x16x32_bf16 v[110:113], v[170:173], v[178:181], v[110:113]
	v_mfma_f32_16x16x32_bf16 v[94:97], v[170:173], v[192:195], v[94:97]
	v_mfma_f32_16x16x32_bf16 v[94:97], v[174:177], v[196:199], v[94:97]
	v_mfma_f32_16x16x32_bf16 v[102:105], v[166:169], v[196:199], v[102:105]
	v_mfma_f32_16x16x32_bf16 v[102:105], v[162:165], v[192:195], v[102:105]
	v_mfma_f32_16x16x32_bf16 v[86:89], v[162:165], v[200:203], v[86:89]
	v_mfma_f32_16x16x32_bf16 v[86:89], v[166:169], v[204:207], v[86:89]
	v_mfma_f32_16x16x32_bf16 v[78:81], v[174:177], v[204:207], v[78:81]
	v_mfma_f32_16x16x32_bf16 v[78:81], v[170:173], v[200:203], v[78:81]
	v_mfma_f32_16x16x32_bf16 v[66:69], v[170:173], v[208:211], v[66:69]
	v_mfma_f32_16x16x32_bf16 v[66:69], v[174:177], v[212:215], v[66:69]
	v_mfma_f32_16x16x32_bf16 v[70:73], v[166:169], v[212:215], v[70:73]
	v_mfma_f32_16x16x32_bf16 v[70:73], v[162:165], v[208:211], v[70:73]
	s_barrier
	s_setprio 0
	s_add_i32 s0, s0, s39
	s_mov_b32 m0, s0
	ds_read_b128 v[178:181], v145 offset:49152
	ds_read_b128 v[182:185], v145 offset:50176
	ds_read_b128 v[192:195], v145 offset:51200
	ds_read_b128 v[196:199], v145 offset:52224
	ds_read_b128 v[200:203], v145 offset:53248
	ds_read_b128 v[204:207], v145 offset:54272
	ds_read_b128 v[208:211], v145 offset:55296
	ds_read_b128 v[212:215], v145 offset:56320
	s_add_u32 s100, s28, 0x80
	s_addc_u32 s101, s29, 0
	global_load_lds_dwordx4 v186, s[100:101]
	s_add_i32 m0, s0, 0x2000
	s_add_u32 s28, s28, 0x80080
	s_addc_u32 s29, s29, 0
	s_add_i32 s0, s1, s39
	s_add_u32 s100, s28, 0xfff80000
	s_addc_u32 s101, s29, -1
	global_load_lds_dwordx4 v130, s[100:101]
	s_mov_b32 m0, s0
	s_nop 0
	global_load_lds_dwordx4 v186, s[28:29]
	s_add_i32 m0, s0, 0x2000
	s_nop 0
	global_load_lds_dwordx4 v130, s[28:29]
	s_mov_b32 m0, s43
	s_nop 0
	s_add_u32 s100, s30, 0xfff80080
	s_addc_u32 s101, s31, -1
	global_load_lds_dwordx4 v134, s[100:101]
	s_mov_b32 m0, s44
	s_nop 0
	s_add_u32 s100, s30, 0xfff80080
	s_addc_u32 s101, s31, -1
	global_load_lds_dwordx4 v132, s[100:101]
	s_waitcnt vmcnt(8)
	s_waitcnt lgkmcnt(0)
	s_setprio 1
	s_barrier

	v_mfma_f32_16x16x32_bf16 v[62:65], v[146:149], v[178:181], v[62:65]
	v_mfma_f32_16x16x32_bf16 v[62:65], v[150:153], v[182:185], v[62:65]
	v_mfma_f32_16x16x32_bf16 v[58:61], v[158:161], v[182:185], v[58:61]
	v_mfma_f32_16x16x32_bf16 v[58:61], v[154:157], v[178:181], v[58:61]
	v_mfma_f32_16x16x32_bf16 v[42:45], v[154:157], v[192:195], v[42:45]
	v_mfma_f32_16x16x32_bf16 v[42:45], v[158:161], v[196:199], v[42:45]
	v_mfma_f32_16x16x32_bf16 v[50:53], v[150:153], v[196:199], v[50:53]
	v_mfma_f32_16x16x32_bf16 v[50:53], v[146:149], v[192:195], v[50:53]
	v_mfma_f32_16x16x32_bf16 v[34:37], v[146:149], v[200:203], v[34:37]
	v_mfma_f32_16x16x32_bf16 v[34:37], v[150:153], v[204:207], v[34:37]
	v_mfma_f32_16x16x32_bf16 v[26:29], v[158:161], v[204:207], v[26:29]
	v_mfma_f32_16x16x32_bf16 v[26:29], v[154:157], v[200:203], v[26:29]
	v_mfma_f32_16x16x32_bf16 v[10:13], v[154:157], v[208:211], v[10:13]
	v_mfma_f32_16x16x32_bf16 v[10:13], v[158:161], v[212:215], v[10:13]
	v_mfma_f32_16x16x32_bf16 v[18:21], v[150:153], v[212:215], v[18:21]
	v_mfma_f32_16x16x32_bf16 v[18:21], v[146:149], v[208:211], v[18:21]


	v_mfma_f32_16x16x32_bf16 v[54:57], v[162:165], v[178:181], v[54:57]
	v_mfma_f32_16x16x32_bf16 v[54:57], v[166:169], v[182:185], v[54:57]
	v_mfma_f32_16x16x32_bf16 v[46:49], v[174:177], v[182:185], v[46:49]
	v_mfma_f32_16x16x32_bf16 v[46:49], v[170:173], v[178:181], v[46:49]
	v_mfma_f32_16x16x32_bf16 v[30:33], v[170:173], v[192:195], v[30:33]
	v_mfma_f32_16x16x32_bf16 v[30:33], v[174:177], v[196:199], v[30:33]
	v_mfma_f32_16x16x32_bf16 v[38:41], v[166:169], v[196:199], v[38:41]
	v_mfma_f32_16x16x32_bf16 v[38:41], v[162:165], v[192:195], v[38:41]
	v_mfma_f32_16x16x32_bf16 v[22:25], v[162:165], v[200:203], v[22:25]
	v_mfma_f32_16x16x32_bf16 v[22:25], v[166:169], v[204:207], v[22:25]
	v_mfma_f32_16x16x32_bf16 v[14:17], v[174:177], v[204:207], v[14:17]
	v_mfma_f32_16x16x32_bf16 v[14:17], v[170:173], v[200:203], v[14:17]
	v_mfma_f32_16x16x32_bf16 v[2:5], v[170:173], v[208:211], v[2:5]
	v_mfma_f32_16x16x32_bf16 v[2:5], v[174:177], v[212:215], v[2:5]
	v_mfma_f32_16x16x32_bf16 v[6:9], v[166:169], v[212:215], v[6:9]
	v_mfma_f32_16x16x32_bf16 v[6:9], v[162:165], v[208:211], v[6:9]
	s_barrier
	s_setprio 0
	s_add_i32 s55, s55, 2
	s_add_u32 s26, s26, 0x100
	s_addc_u32 s27, s27, 0
	s_add_u32 s53, s53, 0x100
	s_addc_u32 s54, s54, 0
	s_cmp_gt_u32 s55, 29
	s_cbranch_scc0 .LBB0_443

.LBB0_1125:
	s_ashr_i32 s19, s18, 31
	s_lshl_b64 s[0:1], s[18:19], 20
	s_add_u32 s20, s3, s0
	s_addc_u32 s21, s36, s1
	s_and_b64 s[0:1], s[4:5], exec
	s_cselect_b32 s19, s21, s29
	s_cselect_b32 s25, s20, s28
	s_ashr_i32 s17, s16, 31
	s_lshl_b64 s[0:1], s[16:17], 20
	s_add_u32 s22, s37, s0
	s_addc_u32 s23, s38, s1
	s_and_b64 s[0:1], s[4:5], exec
	s_cselect_b32 s17, s23, s31
	s_cselect_b32 s27, s22, s30
	s_add_u32 s28, s28, 0x80080
	s_addc_u32 s29, s29, 0
	s_add_u32 s51, s30, 0x100
	s_addc_u32 s52, s31, 0
	s_mov_b32 s53, -2
	s_add_u32 s0, s28, 0xfff80080
	s_addc_u32 s1, s29, -1
	s_add_i32 s54, 0, 0x10000
	s_cmp_eq_u32 s53, 28
	s_cselect_b32 s35, s19, s1
	s_cselect_b32 s34, s25, s0
	s_cselect_b32 s31, s17, s52
	s_cselect_b32 s30, s27, s51
	s_add_i32 s55, 0, 0x14000
	v_add_u32_e32 v126, s54, v237
	v_add_u32_e32 v158, s55, v237
	ds_read_b128 v[90:93], v126
	ds_read_b128 v[102:105], v126 offset:1024
	ds_read_b128 v[114:117], v126 offset:2048
	ds_read_b128 v[126:129], v126 offset:3072
	ds_read_b128 v[138:141], v158
	ds_read_b128 v[142:145], v158 offset:1024
	ds_read_b128 v[154:157], v158 offset:2048
	ds_read_b128 v[158:161], v158 offset:3072
	v_lshl_add_u64 v[188:189], s[28:29], 0, v[198:199]
	s_add_i32 m0, s40, 0xc000
	ds_read_b128 v[162:165], v238
	ds_read_b128 v[166:169], v238 offset:1024
	ds_read_b128 v[170:173], v238 offset:2048
	ds_read_b128 v[174:177], v238 offset:3072
	ds_read_b128 v[178:181], v238 offset:4096
	ds_read_b128 v[182:185], v238 offset:5120
	ds_read_b128 v[202:205], v238 offset:6144
	ds_read_b128 v[206:209], v238 offset:7168
	global_load_lds_dwordx4 v[188:189], off
	v_lshl_add_u64 v[188:189], s[28:29], 0, v[200:201]
	s_add_i32 m0, s40, 0xe000
	s_nop 0
	global_load_lds_dwordx4 v[188:189], off
	s_waitcnt vmcnt(8)
	s_waitcnt lgkmcnt(0)
	s_setprio 1
	s_barrier

	v_mfma_f32_16x16x32_bf16 v[150:153], v[90:93], v[162:165], 0
	v_mfma_f32_16x16x32_bf16 v[150:153], v[102:105], v[166:169], v[150:153]
	v_mfma_f32_16x16x32_bf16 v[146:149], v[126:129], v[166:169], 0
	v_mfma_f32_16x16x32_bf16 v[146:149], v[114:117], v[162:165], v[146:149]
	v_mfma_f32_16x16x32_bf16 v[118:121], v[114:117], v[170:173], 0
	v_mfma_f32_16x16x32_bf16 v[118:121], v[126:129], v[174:177], v[118:121]
	v_mfma_f32_16x16x32_bf16 v[122:125], v[102:105], v[174:177], 0
	v_mfma_f32_16x16x32_bf16 v[122:125], v[90:93], v[170:173], v[122:125]
	v_mfma_f32_16x16x32_bf16 v[98:101], v[90:93], v[178:181], 0
	v_mfma_f32_16x16x32_bf16 v[98:101], v[102:105], v[182:185], v[98:101]
	v_mfma_f32_16x16x32_bf16 v[94:97], v[126:129], v[182:185], 0
	v_mfma_f32_16x16x32_bf16 v[94:97], v[114:117], v[178:181], v[94:97]
	v_mfma_f32_16x16x32_bf16 v[74:77], v[114:117], v[202:205], 0
	v_mfma_f32_16x16x32_bf16 v[74:77], v[126:129], v[206:209], v[74:77]
	v_mfma_f32_16x16x32_bf16 v[78:81], v[102:105], v[206:209], 0
	v_mfma_f32_16x16x32_bf16 v[78:81], v[90:93], v[202:205], v[78:81]


	v_mfma_f32_16x16x32_bf16 v[134:137], v[138:141], v[162:165], 0
	v_mfma_f32_16x16x32_bf16 v[134:137], v[142:145], v[166:169], v[134:137]
	v_mfma_f32_16x16x32_bf16 v[130:133], v[158:161], v[166:169], 0
	v_mfma_f32_16x16x32_bf16 v[130:133], v[154:157], v[162:165], v[130:133]
	v_mfma_f32_16x16x32_bf16 v[106:109], v[154:157], v[170:173], 0
	v_mfma_f32_16x16x32_bf16 v[106:109], v[158:161], v[174:177], v[106:109]
	v_mfma_f32_16x16x32_bf16 v[110:113], v[142:145], v[174:177], 0
	v_mfma_f32_16x16x32_bf16 v[110:113], v[138:141], v[170:173], v[110:113]
	v_mfma_f32_16x16x32_bf16 v[86:89], v[138:141], v[178:181], 0
	v_mfma_f32_16x16x32_bf16 v[86:89], v[142:145], v[182:185], v[86:89]
	v_mfma_f32_16x16x32_bf16 v[82:85], v[158:161], v[182:185], 0
	v_mfma_f32_16x16x32_bf16 v[82:85], v[154:157], v[178:181], v[82:85]
	v_mfma_f32_16x16x32_bf16 v[66:69], v[154:157], v[202:205], 0
	v_mfma_f32_16x16x32_bf16 v[66:69], v[158:161], v[206:209], v[66:69]
	v_mfma_f32_16x16x32_bf16 v[70:73], v[142:145], v[206:209], 0
	v_mfma_f32_16x16x32_bf16 v[70:73], v[138:141], v[202:205], v[70:73]
	s_barrier
	s_setprio 0
	s_add_i32 s0, s54, s39
	v_lshl_add_u64 v[188:189], s[30:31], 0, v[186:187]
	s_mov_b32 m0, s0
	ds_read_b128 v[162:165], v238 offset:16384
	ds_read_b128 v[166:169], v238 offset:17408
	ds_read_b128 v[170:173], v238 offset:18432
	ds_read_b128 v[174:177], v238 offset:19456
	ds_read_b128 v[178:181], v238 offset:20480
	ds_read_b128 v[182:185], v238 offset:21504
	ds_read_b128 v[202:205], v238 offset:22528
	ds_read_b128 v[206:209], v238 offset:23552
	global_load_lds_dwordx4 v[188:189], off
	s_add_i32 m0, s0, 0x2000
	s_add_u32 s0, s30, 0x80000
	v_lshl_add_u64 v[210:211], s[30:31], 0, v[196:197]
	s_addc_u32 s1, s31, 0
	s_add_i32 s54, s55, s39
	global_load_lds_dwordx4 v[210:211], off
	v_lshl_add_u64 v[212:213], s[0:1], 0, v[186:187]
	s_mov_b32 m0, s54
	v_lshl_add_u64 v[214:215], s[34:35], 0, v[194:195]
	global_load_lds_dwordx4 v[212:213], off
	v_lshl_add_u64 v[212:213], s[0:1], 0, v[196:197]
	s_add_i32 m0, s54, 0x2000
	s_nop 0
	global_load_lds_dwordx4 v[212:213], off
	v_lshl_add_u64 v[212:213], s[34:35], 0, v[192:193]
	s_mov_b32 m0, s40
	s_nop 0
	global_load_lds_dwordx4 v[212:213], off
	s_mov_b32 m0, s41
	s_nop 0
	global_load_lds_dwordx4 v[214:215], off
	s_waitcnt vmcnt(8)
	s_waitcnt lgkmcnt(0)
	s_setprio 1
	s_barrier

	v_mfma_f32_16x16x32_bf16 v[62:65], v[90:93], v[162:165], 0
	v_mfma_f32_16x16x32_bf16 v[62:65], v[102:105], v[166:169], v[62:65]
	v_mfma_f32_16x16x32_bf16 v[58:61], v[126:129], v[166:169], 0
	v_mfma_f32_16x16x32_bf16 v[58:61], v[114:117], v[162:165], v[58:61]
	v_mfma_f32_16x16x32_bf16 v[42:45], v[114:117], v[170:173], 0
	v_mfma_f32_16x16x32_bf16 v[42:45], v[126:129], v[174:177], v[42:45]
	v_mfma_f32_16x16x32_bf16 v[46:49], v[102:105], v[174:177], 0
	v_mfma_f32_16x16x32_bf16 v[46:49], v[90:93], v[170:173], v[46:49]
	v_mfma_f32_16x16x32_bf16 v[30:33], v[90:93], v[178:181], 0
	v_mfma_f32_16x16x32_bf16 v[30:33], v[102:105], v[182:185], v[30:33]
	v_mfma_f32_16x16x32_bf16 v[26:29], v[126:129], v[182:185], 0
	v_mfma_f32_16x16x32_bf16 v[26:29], v[114:117], v[178:181], v[26:29]
	v_mfma_f32_16x16x32_bf16 v[10:13], v[114:117], v[202:205], 0
	v_mfma_f32_16x16x32_bf16 v[10:13], v[126:129], v[206:209], v[10:13]
	v_mfma_f32_16x16x32_bf16 v[14:17], v[102:105], v[206:209], 0
	v_mfma_f32_16x16x32_bf16 v[14:17], v[90:93], v[202:205], v[14:17]


	v_mfma_f32_16x16x32_bf16 v[54:57], v[138:141], v[162:165], 0
	v_mfma_f32_16x16x32_bf16 v[54:57], v[142:145], v[166:169], v[54:57]
	v_mfma_f32_16x16x32_bf16 v[50:53], v[158:161], v[166:169], 0
	v_mfma_f32_16x16x32_bf16 v[50:53], v[154:157], v[162:165], v[50:53]
	v_mfma_f32_16x16x32_bf16 v[34:37], v[154:157], v[170:173], 0
	v_mfma_f32_16x16x32_bf16 v[34:37], v[158:161], v[174:177], v[34:37]
	v_mfma_f32_16x16x32_bf16 v[38:41], v[142:145], v[174:177], 0
	v_mfma_f32_16x16x32_bf16 v[38:41], v[138:141], v[170:173], v[38:41]
	v_mfma_f32_16x16x32_bf16 v[22:25], v[138:141], v[178:181], 0
	v_mfma_f32_16x16x32_bf16 v[22:25], v[142:145], v[182:185], v[22:25]
	v_mfma_f32_16x16x32_bf16 v[18:21], v[158:161], v[182:185], 0
	v_mfma_f32_16x16x32_bf16 v[18:21], v[154:157], v[178:181], v[18:21]
	v_mfma_f32_16x16x32_bf16 v[2:5], v[154:157], v[202:205], 0
	v_mfma_f32_16x16x32_bf16 v[2:5], v[158:161], v[206:209], v[2:5]
	v_mfma_f32_16x16x32_bf16 v[6:9], v[142:145], v[206:209], 0
	v_mfma_f32_16x16x32_bf16 v[6:9], v[138:141], v[202:205], v[6:9]
	s_barrier
	s_setprio 0
	s_add_i32 s54, 0, 0x18000
	s_add_i32 s55, 0, 0x1c000
	v_add_u32_e32 v126, s54, v237
	v_add_u32_e32 v158, s55, v237
	ds_read_b128 v[90:93], v126
	ds_read_b128 v[102:105], v126 offset:1024
	ds_read_b128 v[114:117], v126 offset:2048
	ds_read_b128 v[126:129], v126 offset:3072
	ds_read_b128 v[138:141], v158
	ds_read_b128 v[142:145], v158 offset:1024
	ds_read_b128 v[154:157], v158 offset:2048
	ds_read_b128 v[158:161], v158 offset:3072
	s_add_u32 s0, s34, 0x80000
	s_addc_u32 s1, s35, 0
	s_mov_b32 m0, s42
	v_lshl_add_u64 v[216:217], s[0:1], 0, v[192:193]
	ds_read_b128 v[162:165], v238 offset:32768
	ds_read_b128 v[166:169], v238 offset:33792
	ds_read_b128 v[170:173], v238 offset:34816
	ds_read_b128 v[174:177], v238 offset:35840
	ds_read_b128 v[178:181], v238 offset:36864
	ds_read_b128 v[182:185], v238 offset:37888
	ds_read_b128 v[202:205], v238 offset:38912
	ds_read_b128 v[206:209], v238 offset:39936
	global_load_lds_dwordx4 v[216:217], off
	v_lshl_add_u64 v[216:217], s[0:1], 0, v[194:195]
	s_mov_b32 m0, s43
	s_nop 0
	global_load_lds_dwordx4 v[216:217], off
	s_waitcnt vmcnt(8)
	s_waitcnt lgkmcnt(0)
	s_setprio 1
	s_barrier

	v_mfma_f32_16x16x32_bf16 v[150:153], v[90:93], v[162:165], v[150:153]
	v_mfma_f32_16x16x32_bf16 v[150:153], v[102:105], v[166:169], v[150:153]
	v_mfma_f32_16x16x32_bf16 v[146:149], v[126:129], v[166:169], v[146:149]
	v_mfma_f32_16x16x32_bf16 v[146:149], v[114:117], v[162:165], v[146:149]
	v_mfma_f32_16x16x32_bf16 v[118:121], v[114:117], v[170:173], v[118:121]
	v_mfma_f32_16x16x32_bf16 v[118:121], v[126:129], v[174:177], v[118:121]
	v_mfma_f32_16x16x32_bf16 v[122:125], v[102:105], v[174:177], v[122:125]
	v_mfma_f32_16x16x32_bf16 v[122:125], v[90:93], v[170:173], v[122:125]
	v_mfma_f32_16x16x32_bf16 v[98:101], v[90:93], v[178:181], v[98:101]
	v_mfma_f32_16x16x32_bf16 v[98:101], v[102:105], v[182:185], v[98:101]
	v_mfma_f32_16x16x32_bf16 v[94:97], v[126:129], v[182:185], v[94:97]
	v_mfma_f32_16x16x32_bf16 v[94:97], v[114:117], v[178:181], v[94:97]
	v_mfma_f32_16x16x32_bf16 v[74:77], v[114:117], v[202:205], v[74:77]
	v_mfma_f32_16x16x32_bf16 v[74:77], v[126:129], v[206:209], v[74:77]
	v_mfma_f32_16x16x32_bf16 v[78:81], v[102:105], v[206:209], v[78:81]
	v_mfma_f32_16x16x32_bf16 v[78:81], v[90:93], v[202:205], v[78:81]


	v_mfma_f32_16x16x32_bf16 v[134:137], v[138:141], v[162:165], v[134:137]
	v_mfma_f32_16x16x32_bf16 v[134:137], v[142:145], v[166:169], v[134:137]
	v_mfma_f32_16x16x32_bf16 v[130:133], v[158:161], v[166:169], v[130:133]
	v_mfma_f32_16x16x32_bf16 v[130:133], v[154:157], v[162:165], v[130:133]
	v_mfma_f32_16x16x32_bf16 v[106:109], v[154:157], v[170:173], v[106:109]
	v_mfma_f32_16x16x32_bf16 v[106:109], v[158:161], v[174:177], v[106:109]
	v_mfma_f32_16x16x32_bf16 v[110:113], v[142:145], v[174:177], v[110:113]
	v_mfma_f32_16x16x32_bf16 v[110:113], v[138:141], v[170:173], v[110:113]
	v_mfma_f32_16x16x32_bf16 v[86:89], v[138:141], v[178:181], v[86:89]
	v_mfma_f32_16x16x32_bf16 v[86:89], v[142:145], v[182:185], v[86:89]
	v_mfma_f32_16x16x32_bf16 v[82:85], v[158:161], v[182:185], v[82:85]
	v_mfma_f32_16x16x32_bf16 v[82:85], v[154:157], v[178:181], v[82:85]
	v_mfma_f32_16x16x32_bf16 v[66:69], v[154:157], v[202:205], v[66:69]
	v_mfma_f32_16x16x32_bf16 v[66:69], v[158:161], v[206:209], v[66:69]
	v_mfma_f32_16x16x32_bf16 v[70:73], v[142:145], v[206:209], v[70:73]
	v_mfma_f32_16x16x32_bf16 v[70:73], v[138:141], v[202:205], v[70:73]
	s_barrier
	s_setprio 0
	s_add_i32 s0, s54, s39
	v_lshl_add_u64 v[188:189], v[188:189], 0, s[84:85]
	s_mov_b32 m0, s0
	ds_read_b128 v[162:165], v238 offset:49152
	ds_read_b128 v[166:169], v238 offset:50176
	ds_read_b128 v[170:173], v238 offset:51200
	ds_read_b128 v[174:177], v238 offset:52224
	ds_read_b128 v[178:181], v238 offset:53248
	ds_read_b128 v[182:185], v238 offset:54272
	ds_read_b128 v[202:205], v238 offset:55296
	ds_read_b128 v[206:209], v238 offset:56320
	global_load_lds_dwordx4 v[188:189], off
	s_add_i32 m0, s0, 0x2000
	s_add_u32 s0, s30, 0x80080
	v_lshl_add_u64 v[188:189], v[210:211], 0, s[84:85]
	s_addc_u32 s1, s31, 0
	s_add_i32 s30, s55, s39
	global_load_lds_dwordx4 v[188:189], off
	v_lshl_add_u64 v[188:189], s[0:1], 0, v[186:187]
	s_mov_b32 m0, s30
	s_nop 0
	global_load_lds_dwordx4 v[188:189], off
	v_lshl_add_u64 v[188:189], s[0:1], 0, v[196:197]
	s_add_i32 m0, s30, 0x2000
	s_nop 0
	global_load_lds_dwordx4 v[188:189], off
	v_lshl_add_u64 v[188:189], v[212:213], 0, s[84:85]
	s_mov_b32 m0, s47
	s_nop 0
	global_load_lds_dwordx4 v[188:189], off
	v_lshl_add_u64 v[188:189], v[214:215], 0, s[84:85]
	s_mov_b32 m0, s48
	s_nop 0
	global_load_lds_dwordx4 v[188:189], off
	s_waitcnt vmcnt(8)
	s_waitcnt lgkmcnt(0)
	s_setprio 1
	s_barrier

	v_mfma_f32_16x16x32_bf16 v[62:65], v[90:93], v[162:165], v[62:65]
	v_mfma_f32_16x16x32_bf16 v[62:65], v[102:105], v[166:169], v[62:65]
	v_mfma_f32_16x16x32_bf16 v[58:61], v[126:129], v[166:169], v[58:61]
	v_mfma_f32_16x16x32_bf16 v[58:61], v[114:117], v[162:165], v[58:61]
	v_mfma_f32_16x16x32_bf16 v[42:45], v[114:117], v[170:173], v[42:45]
	v_mfma_f32_16x16x32_bf16 v[42:45], v[126:129], v[174:177], v[42:45]
	v_mfma_f32_16x16x32_bf16 v[46:49], v[102:105], v[174:177], v[46:49]
	v_mfma_f32_16x16x32_bf16 v[46:49], v[90:93], v[170:173], v[46:49]
	v_mfma_f32_16x16x32_bf16 v[30:33], v[90:93], v[178:181], v[30:33]
	v_mfma_f32_16x16x32_bf16 v[30:33], v[102:105], v[182:185], v[30:33]
	v_mfma_f32_16x16x32_bf16 v[26:29], v[126:129], v[182:185], v[26:29]
	v_mfma_f32_16x16x32_bf16 v[26:29], v[114:117], v[178:181], v[26:29]
	v_mfma_f32_16x16x32_bf16 v[10:13], v[114:117], v[202:205], v[10:13]
	v_mfma_f32_16x16x32_bf16 v[10:13], v[126:129], v[206:209], v[10:13]
	v_mfma_f32_16x16x32_bf16 v[14:17], v[102:105], v[206:209], v[14:17]
	v_mfma_f32_16x16x32_bf16 v[14:17], v[90:93], v[202:205], v[14:17]


	v_mfma_f32_16x16x32_bf16 v[54:57], v[138:141], v[162:165], v[54:57]
	v_mfma_f32_16x16x32_bf16 v[54:57], v[142:145], v[166:169], v[54:57]
	v_mfma_f32_16x16x32_bf16 v[50:53], v[158:161], v[166:169], v[50:53]
	v_mfma_f32_16x16x32_bf16 v[50:53], v[154:157], v[162:165], v[50:53]
	v_mfma_f32_16x16x32_bf16 v[34:37], v[154:157], v[170:173], v[34:37]
	v_mfma_f32_16x16x32_bf16 v[34:37], v[158:161], v[174:177], v[34:37]
	v_mfma_f32_16x16x32_bf16 v[38:41], v[142:145], v[174:177], v[38:41]
	v_mfma_f32_16x16x32_bf16 v[38:41], v[138:141], v[170:173], v[38:41]
	v_mfma_f32_16x16x32_bf16 v[22:25], v[138:141], v[178:181], v[22:25]
	v_mfma_f32_16x16x32_bf16 v[22:25], v[142:145], v[182:185], v[22:25]
	v_mfma_f32_16x16x32_bf16 v[18:21], v[158:161], v[182:185], v[18:21]
	v_mfma_f32_16x16x32_bf16 v[18:21], v[154:157], v[178:181], v[18:21]
	v_mfma_f32_16x16x32_bf16 v[2:5], v[154:157], v[202:205], v[2:5]
	v_mfma_f32_16x16x32_bf16 v[2:5], v[158:161], v[206:209], v[2:5]
	v_mfma_f32_16x16x32_bf16 v[6:9], v[142:145], v[206:209], v[6:9]
	v_mfma_f32_16x16x32_bf16 v[6:9], v[138:141], v[202:205], v[6:9]
	s_barrier
	s_setprio 0
	s_add_i32 s53, s53, 2
	s_add_u32 s28, s28, 0x100
	s_addc_u32 s29, s29, 0
	s_add_u32 s51, s51, 0x100
	s_addc_u32 s52, s52, 0
	s_cmp_gt_u32 s53, 29
	s_cbranch_scc0 .LBB0_1126
